# v014 + accumulator zero-init between GEMM units as 64 v_mov_b64 instead of 128 v_mov_b32 (P1/P5/P6 sites)
# baseline (speedup 1.0000x reference)
.LBB0_150:
	s_ashr_i32 s47, s46, 31
	s_lshl_b64 s[8:9], s[46:47], 19
	s_add_u32 s50, s43, s8
	s_addc_u32 s51, s68, s9
	s_and_b64 s[8:9], s[48:49], exec
	s_cselect_b32 s3, s51, s1
	s_cselect_b32 s33, s50, s0
	s_ashr_i32 s45, s44, 31
	s_lshl_b64 s[8:9], s[44:45], 19
	s_add_u32 s52, s69, s8
	s_addc_u32 s53, s70, s9
	s_and_b64 s[8:9], s[48:49], exec
	s_cselect_b32 s45, s53, s7
	s_cselect_b32 s47, s52, s6
	s_add_u32 s0, s0, 0x40080
	s_addc_u32 s1, s1, 0
	s_add_u32 s56, s6, 0x100
	v_mov_b64_e32 v[2:3], 0
	v_mov_b64_e32 v[4:5], 0
	v_mov_b64_e32 v[6:7], 0
	v_mov_b64_e32 v[8:9], 0
	v_mov_b64_e32 v[10:11], 0
	v_mov_b64_e32 v[12:13], 0
	v_mov_b64_e32 v[14:15], 0
	v_mov_b64_e32 v[16:17], 0
	v_mov_b64_e32 v[18:19], 0
	v_mov_b64_e32 v[20:21], 0
	v_mov_b64_e32 v[22:23], 0
	v_mov_b64_e32 v[24:25], 0
	v_mov_b64_e32 v[26:27], 0
	v_mov_b64_e32 v[28:29], 0
	v_mov_b64_e32 v[30:31], 0
	v_mov_b64_e32 v[32:33], 0
	v_mov_b64_e32 v[34:35], 0
	v_mov_b64_e32 v[36:37], 0
	v_mov_b64_e32 v[38:39], 0
	v_mov_b64_e32 v[40:41], 0
	v_mov_b64_e32 v[42:43], 0
	v_mov_b64_e32 v[44:45], 0
	v_mov_b64_e32 v[46:47], 0
	v_mov_b64_e32 v[48:49], 0
	v_mov_b64_e32 v[50:51], 0
	v_mov_b64_e32 v[52:53], 0
	v_mov_b64_e32 v[54:55], 0
	v_mov_b64_e32 v[56:57], 0
	v_mov_b64_e32 v[58:59], 0
	v_mov_b64_e32 v[60:61], 0
	v_mov_b64_e32 v[62:63], 0
	v_mov_b64_e32 v[64:65], 0
	v_mov_b64_e32 v[66:67], 0
	v_mov_b64_e32 v[68:69], 0
	v_mov_b64_e32 v[70:71], 0
	v_mov_b64_e32 v[72:73], 0
	v_mov_b64_e32 v[74:75], 0
	v_mov_b64_e32 v[76:77], 0
	v_mov_b64_e32 v[78:79], 0
	v_mov_b64_e32 v[80:81], 0
	v_mov_b64_e32 v[82:83], 0
	v_mov_b64_e32 v[84:85], 0
	v_mov_b64_e32 v[86:87], 0
	v_mov_b64_e32 v[88:89], 0
	v_mov_b64_e32 v[90:91], 0
	v_mov_b64_e32 v[92:93], 0
	v_mov_b64_e32 v[94:95], 0
	v_mov_b64_e32 v[96:97], 0
	v_mov_b64_e32 v[98:99], 0
	v_mov_b64_e32 v[100:101], 0
	v_mov_b64_e32 v[102:103], 0
	v_mov_b64_e32 v[104:105], 0
	v_mov_b64_e32 v[106:107], 0
	v_mov_b64_e32 v[108:109], 0
	v_mov_b64_e32 v[110:111], 0
	v_mov_b64_e32 v[112:113], 0
	v_mov_b64_e32 v[114:115], 0
	v_mov_b64_e32 v[116:117], 0
	v_mov_b64_e32 v[118:119], 0
	v_mov_b64_e32 v[120:121], 0
	v_mov_b64_e32 v[122:123], 0
	v_mov_b64_e32 v[124:125], 0
	v_mov_b64_e32 v[126:127], 0
	v_mov_b64_e32 v[128:129], 0
	s_addc_u32 s57, s7, 0
	s_mov_b32 s58, -2
	s_waitcnt lgkmcnt(0)
	s_waitcnt vmcnt(0)

.LBB0_844:
	s_ashr_i32 s19, s18, 31
	s_lshl_b64 s[20:21], s[18:19], 19
	s_add_u32 s20, s33, s20
	s_addc_u32 s21, s36, s21
	s_and_b64 s[22:23], s[4:5], exec
	s_cselect_b32 s19, s21, s29
	s_cselect_b32 s25, s20, s28
	s_ashr_i32 s17, s16, 31
	s_lshl_b64 s[22:23], s[16:17], 19
	s_add_u32 s22, s37, s22
	s_addc_u32 s23, s38, s23
	s_and_b64 s[34:35], s[4:5], exec
	s_cselect_b32 s17, s23, s31
	s_cselect_b32 s51, s22, s30
	s_add_u32 s28, s28, 0x40080
	s_addc_u32 s29, s29, 0
	s_add_u32 s52, s30, 0x100
	v_mov_b64_e32 v[2:3], 0
	v_mov_b64_e32 v[4:5], 0
	v_mov_b64_e32 v[6:7], 0
	v_mov_b64_e32 v[8:9], 0
	v_mov_b64_e32 v[10:11], 0
	v_mov_b64_e32 v[12:13], 0
	v_mov_b64_e32 v[14:15], 0
	v_mov_b64_e32 v[16:17], 0
	v_mov_b64_e32 v[18:19], 0
	v_mov_b64_e32 v[20:21], 0
	v_mov_b64_e32 v[22:23], 0
	v_mov_b64_e32 v[24:25], 0
	v_mov_b64_e32 v[26:27], 0
	v_mov_b64_e32 v[28:29], 0
	v_mov_b64_e32 v[30:31], 0
	v_mov_b64_e32 v[32:33], 0
	v_mov_b64_e32 v[34:35], 0
	v_mov_b64_e32 v[36:37], 0
	v_mov_b64_e32 v[38:39], 0
	v_mov_b64_e32 v[40:41], 0
	v_mov_b64_e32 v[42:43], 0
	v_mov_b64_e32 v[44:45], 0
	v_mov_b64_e32 v[46:47], 0
	v_mov_b64_e32 v[48:49], 0
	v_mov_b64_e32 v[50:51], 0
	v_mov_b64_e32 v[52:53], 0
	v_mov_b64_e32 v[54:55], 0
	v_mov_b64_e32 v[56:57], 0
	v_mov_b64_e32 v[58:59], 0
	v_mov_b64_e32 v[60:61], 0
	v_mov_b64_e32 v[62:63], 0
	v_mov_b64_e32 v[64:65], 0
	v_mov_b64_e32 v[66:67], 0
	v_mov_b64_e32 v[68:69], 0
	v_mov_b64_e32 v[70:71], 0
	v_mov_b64_e32 v[72:73], 0
	v_mov_b64_e32 v[74:75], 0
	v_mov_b64_e32 v[76:77], 0
	v_mov_b64_e32 v[78:79], 0
	v_mov_b64_e32 v[80:81], 0
	v_mov_b64_e32 v[82:83], 0
	v_mov_b64_e32 v[84:85], 0
	v_mov_b64_e32 v[86:87], 0
	v_mov_b64_e32 v[88:89], 0
	v_mov_b64_e32 v[90:91], 0
	v_mov_b64_e32 v[92:93], 0
	v_mov_b64_e32 v[94:95], 0
	v_mov_b64_e32 v[96:97], 0
	v_mov_b64_e32 v[98:99], 0
	v_mov_b64_e32 v[100:101], 0
	v_mov_b64_e32 v[102:103], 0
	v_mov_b64_e32 v[104:105], 0
	v_mov_b64_e32 v[106:107], 0
	v_mov_b64_e32 v[108:109], 0
	v_mov_b64_e32 v[110:111], 0
	v_mov_b64_e32 v[112:113], 0
	v_mov_b64_e32 v[114:115], 0
	v_mov_b64_e32 v[116:117], 0
	v_mov_b64_e32 v[118:119], 0
	v_mov_b64_e32 v[120:121], 0
	v_mov_b64_e32 v[122:123], 0
	v_mov_b64_e32 v[124:125], 0
	v_mov_b64_e32 v[126:127], 0
	v_mov_b64_e32 v[128:129], 0
	s_addc_u32 s53, s31, 0
	s_mov_b32 s54, -2
	s_waitcnt lgkmcnt(0)

.LBB0_955:
	s_ashr_i32 s29, s28, 31
	s_lshl_b64 s[30:31], s[28:29], 19
	s_add_u32 s30, s40, s30
	s_addc_u32 s31, s41, s31
	s_and_b64 s[34:35], s[0:1], exec
	s_cselect_b32 s29, s31, s7
	s_cselect_b32 s61, s30, s6
	s_ashr_i32 s27, s26, 31
	s_lshl_b64 s[34:35], s[26:27], 19
	s_add_u32 s34, s42, s34
	s_addc_u32 s35, s43, s35
	s_and_b64 s[38:39], s[0:1], exec
	s_cselect_b32 s27, s35, s37
	s_cselect_b32 s62, s34, s36
	s_add_u32 s6, s6, 0x40080
	s_addc_u32 s7, s7, 0
	s_add_u32 s63, s36, 0x100
	v_mov_b64_e32 v[2:3], 0
	v_mov_b64_e32 v[4:5], 0
	v_mov_b64_e32 v[6:7], 0
	v_mov_b64_e32 v[8:9], 0
	v_mov_b64_e32 v[10:11], 0
	v_mov_b64_e32 v[12:13], 0
	v_mov_b64_e32 v[14:15], 0
	v_mov_b64_e32 v[16:17], 0
	v_mov_b64_e32 v[18:19], 0
	v_mov_b64_e32 v[20:21], 0
	v_mov_b64_e32 v[22:23], 0
	v_mov_b64_e32 v[24:25], 0
	v_mov_b64_e32 v[26:27], 0
	v_mov_b64_e32 v[28:29], 0
	v_mov_b64_e32 v[30:31], 0
	v_mov_b64_e32 v[32:33], 0
	v_mov_b64_e32 v[34:35], 0
	v_mov_b64_e32 v[36:37], 0
	v_mov_b64_e32 v[38:39], 0
	v_mov_b64_e32 v[40:41], 0
	v_mov_b64_e32 v[42:43], 0
	v_mov_b64_e32 v[44:45], 0
	v_mov_b64_e32 v[46:47], 0
	v_mov_b64_e32 v[48:49], 0
	v_mov_b64_e32 v[50:51], 0
	v_mov_b64_e32 v[52:53], 0
	v_mov_b64_e32 v[54:55], 0
	v_mov_b64_e32 v[56:57], 0
	v_mov_b64_e32 v[58:59], 0
	v_mov_b64_e32 v[60:61], 0
	v_mov_b64_e32 v[62:63], 0
	v_mov_b64_e32 v[64:65], 0
	v_mov_b64_e32 v[66:67], 0
	v_mov_b64_e32 v[68:69], 0
	v_mov_b64_e32 v[70:71], 0
	v_mov_b64_e32 v[72:73], 0
	v_mov_b64_e32 v[74:75], 0
	v_mov_b64_e32 v[76:77], 0
	v_mov_b64_e32 v[78:79], 0
	v_mov_b64_e32 v[80:81], 0
	v_mov_b64_e32 v[82:83], 0
	v_mov_b64_e32 v[84:85], 0
	v_mov_b64_e32 v[86:87], 0
	v_mov_b64_e32 v[88:89], 0
	v_mov_b64_e32 v[90:91], 0
	v_mov_b64_e32 v[92:93], 0
	v_mov_b64_e32 v[94:95], 0
	v_mov_b64_e32 v[96:97], 0
	v_mov_b64_e32 v[98:99], 0
	v_mov_b64_e32 v[100:101], 0
	v_mov_b64_e32 v[102:103], 0
	v_mov_b64_e32 v[104:105], 0
	v_mov_b64_e32 v[106:107], 0
	v_mov_b64_e32 v[108:109], 0
	v_mov_b64_e32 v[110:111], 0
	v_mov_b64_e32 v[112:113], 0
	v_mov_b64_e32 v[114:115], 0
	v_mov_b64_e32 v[116:117], 0
	v_mov_b64_e32 v[118:119], 0
	v_mov_b64_e32 v[120:121], 0
	v_mov_b64_e32 v[122:123], 0
	v_mov_b64_e32 v[124:125], 0
	v_mov_b64_e32 v[126:127], 0
	v_mov_b64_e32 v[128:129], 0
	s_addc_u32 s64, s37, 0
	s_mov_b32 s65, -2
